# v47 + P6 EpiAct: per-element f32 muls/adds issued as packed v_pk_mul_f32/v_pk_add_f32 (same f32 arithmetic, fewer VALU issue cycles)
# speedup vs baseline: 1.0039x; 1.0027x over previous
; __device__ __forceinline__ unsigned cvt_pk_bf16(float lo, float hi) { unsigned r; asm volatile("v_cvt_pk_bf16_f32 %0, %1, %2" : "=v"(r) : "v"(lo), "v"(hi)); return r; }
; #define LAS __attribute__((address_space(3)))
; __device__ __forceinline__ float rstd_of(float ss) { return __builtin_amdgcn_rsqf(ss * (1.0f / DM) + EPS); }
; __device__ __forceinline__ float siluf_(float x) { return x * __builtin_amdgcn_rcpf(1.0f + __builtin_amdgcn_exp2f(-1.4426950408889634f * x)); }
;     __device__ __forceinline__ void operator()(const pg8::f32x4 (&acc)[2][2][4][2], const Unit& u, int wr, int wc, int fr, int fq) const {
;     ...
;             for (int m = 0; m < 4; ++m) { const int rg = ai * HALF + m * 16; const float rs = rstd_of(SS1[row0 + rg + fr]);
;                 const pg8::f32x4 g0 = acc[ai][0][m][0] * rs, g1 = acc[ai][0][m][1] * rs, u0 = acc[ai][1][m][0] * rs, u1 = acc[ai][1][m][1] * rs;
;                 u32x4 w; w.x = cvt_pk_bf16(siluf_(g0[0]) * u0[0], siluf_(g0[1]) * u0[1]); w.y = cvt_pk_bf16(siluf_(g0[2]) * u0[2], siluf_(g0[3]) * u0[3]);
;                 w.z = cvt_pk_bf16(siluf_(g1[0]) * u1[0], siluf_(g1[1]) * u1[1]); w.w = cvt_pk_bf16(siluf_(g1[2]) * u1[2], siluf_(g1[3]) * u1[3]);
;                 *(LAS u32x4*)epi_slot(W, fr, fq + 4 * (m & 1)) = w;
.LBB0_880:
	s_lshl_b32 s4, s4, 8
	s_add_i32 s21, s4, s42
	v_or_b32_e32 v148, s21, v152
	v_ashrrev_i32_e32 v149, 31, v148
	v_lshl_add_u64 v[150:151], v[148:149], 2, s[14:15]
	v_lshlrev_b32_e32 v208, 2, v152
	v_add_u32_e32 v209, 64, v208
	v_add_u32_e32 v210, 0x80, v208
	v_add_u32_e32 v211, 0xc0, v208
	ds_bpermute_b32 v200, v208, v234
	ds_bpermute_b32 v201, v209, v234
	ds_bpermute_b32 v202, v210, v234
	ds_bpermute_b32 v203, v211, v234
	ds_bpermute_b32 v204, v208, v235
	ds_bpermute_b32 v205, v209, v235
	ds_bpermute_b32 v206, v210, v235
	ds_bpermute_b32 v207, v211, v235
	v_mov_b32_e32 v212, 0xbfb8aa3b
	v_mov_b32_e32 v214, 1.0
	v_mov_b64_e32 v[164:165], s[56:57]
	s_lshl_b32 s4, s5, 7
	s_ashr_i32 s5, s4, 31
	s_waitcnt lgkmcnt(0)
	v_fmamk_f32 v149, v200, 0x3a800000, v159
	v_rsq_f32_e32 v166, v149
	v_or_b32_e32 v149, s21, v153
	v_pk_mul_f32 v[124:125], v[124:125], v[166:167] op_sel_hi:[1,0]
	v_pk_mul_f32 v[128:129], v[128:129], v[166:167] op_sel_hi:[1,0]
	v_pk_mul_f32 v[126:127], v[126:127], v[166:167] op_sel_hi:[1,0]
	v_pk_mul_f32 v[122:123], v[122:123], v[166:167] op_sel_hi:[1,0]
	v_pk_mul_f32 v[120:121], v[120:121], v[166:167] op_sel_hi:[1,0]
	v_pk_mul_f32 v[118:119], v[118:119], v[166:167] op_sel_hi:[1,0]
	v_pk_mul_f32 v[116:117], v[116:117], v[166:167] op_sel_hi:[1,0]
	v_pk_mul_f32 v[114:115], v[114:115], v[166:167] op_sel_hi:[1,0]
	v_pk_mul_f32 v[216:217], v[122:123], v[212:213] op_sel_hi:[1,0]
	v_pk_mul_f32 v[218:219], v[124:125], v[212:213] op_sel_hi:[1,0]
	v_pk_mul_f32 v[220:221], v[126:127], v[212:213] op_sel_hi:[1,0]
	v_pk_mul_f32 v[222:223], v[128:129], v[212:213] op_sel_hi:[1,0]
	v_exp_f32_e32 v219, v219
	v_exp_f32_e32 v220, v220
	v_exp_f32_e32 v221, v221
	v_exp_f32_e32 v222, v222
	v_exp_f32_e32 v223, v223
	v_exp_f32_e32 v216, v216
	v_exp_f32_e32 v217, v217
	v_exp_f32_e32 v218, v218
	v_pk_add_f32 v[220:221], v[220:221], v[214:215] op_sel_hi:[1,0]
	v_pk_add_f32 v[222:223], v[222:223], v[214:215] op_sel_hi:[1,0]
	v_pk_add_f32 v[216:217], v[216:217], v[214:215] op_sel_hi:[1,0]
	v_pk_add_f32 v[218:219], v[218:219], v[214:215] op_sel_hi:[1,0]
	v_rcp_f32_e32 v219, v219
	v_rcp_f32_e32 v220, v220
	v_rcp_f32_e32 v221, v221
	v_rcp_f32_e32 v222, v222
	v_rcp_f32_e32 v223, v223
	v_rcp_f32_e32 v216, v216
	v_rcp_f32_e32 v217, v217
	v_rcp_f32_e32 v218, v218
	v_pk_mul_f32 v[126:127], v[126:127], v[220:221]
	v_pk_mul_f32 v[128:129], v[128:129], v[222:223]
	v_pk_mul_f32 v[122:123], v[122:123], v[216:217]
	v_pk_mul_f32 v[124:125], v[124:125], v[218:219]
	v_pk_mul_f32 v[122:123], v[114:115], v[122:123]
	v_pk_mul_f32 v[116:117], v[116:117], v[124:125]
	v_pk_mul_f32 v[118:119], v[118:119], v[126:127]
	v_pk_mul_f32 v[120:121], v[120:121], v[128:129]
	v_cvt_pk_bf16_f32 v114, v118, v119
	v_cvt_pk_bf16_f32 v115, v120, v121
	v_cvt_pk_bf16_f32 v117, v116, v117
	v_cvt_pk_bf16_f32 v116, v122, v123
	ds_write_b128 v160, v[114:117]
	ds_read_b128 v[116:119], v161
	v_mad_i64_i32 v[114:115], s[28:29], v149, s55, v[164:165]
	v_lshl_add_u64 v[114:115], s[4:5], 1, v[114:115]
	v_lshl_add_u64 v[114:115], v[114:115], 0, s[6:7]
	v_lshl_add_u64 v[114:115], v[114:115], 0, v[138:139]
	s_waitcnt lgkmcnt(0)
	global_store_dwordx4 v[114:115], v[116:119], off
	s_nop 1
	v_fmamk_f32 v116, v201, 0x3a800000, v159
	v_rsq_f32_e32 v116, v116
	s_nop 0
	v_pk_mul_f32 v[108:109], v[108:109], v[116:117] op_sel_hi:[1,0]
	v_pk_mul_f32 v[112:113], v[112:113], v[116:117] op_sel_hi:[1,0]
	v_pk_mul_f32 v[110:111], v[110:111], v[116:117] op_sel_hi:[1,0]
	v_pk_mul_f32 v[106:107], v[106:107], v[116:117] op_sel_hi:[1,0]
	v_pk_mul_f32 v[104:105], v[104:105], v[116:117] op_sel_hi:[1,0]
	v_pk_mul_f32 v[102:103], v[102:103], v[116:117] op_sel_hi:[1,0]
	v_pk_mul_f32 v[100:101], v[100:101], v[116:117] op_sel_hi:[1,0]
	v_pk_mul_f32 v[98:99], v[98:99], v[116:117] op_sel_hi:[1,0]
	v_pk_mul_f32 v[216:217], v[106:107], v[212:213] op_sel_hi:[1,0]
	v_pk_mul_f32 v[218:219], v[108:109], v[212:213] op_sel_hi:[1,0]
	v_pk_mul_f32 v[220:221], v[110:111], v[212:213] op_sel_hi:[1,0]
	v_pk_mul_f32 v[222:223], v[112:113], v[212:213] op_sel_hi:[1,0]
	v_exp_f32_e32 v219, v219
	v_exp_f32_e32 v220, v220
	v_exp_f32_e32 v221, v221
	v_exp_f32_e32 v222, v222
	v_exp_f32_e32 v223, v223
	v_exp_f32_e32 v216, v216
	v_exp_f32_e32 v217, v217
	v_exp_f32_e32 v218, v218
	v_pk_add_f32 v[220:221], v[220:221], v[214:215] op_sel_hi:[1,0]
	v_pk_add_f32 v[222:223], v[222:223], v[214:215] op_sel_hi:[1,0]
	v_pk_add_f32 v[216:217], v[216:217], v[214:215] op_sel_hi:[1,0]
	v_pk_add_f32 v[218:219], v[218:219], v[214:215] op_sel_hi:[1,0]
	v_rcp_f32_e32 v219, v219
	v_rcp_f32_e32 v220, v220
	v_rcp_f32_e32 v221, v221
	v_rcp_f32_e32 v222, v222
	v_rcp_f32_e32 v223, v223
	v_rcp_f32_e32 v216, v216
	v_rcp_f32_e32 v217, v217
	v_rcp_f32_e32 v218, v218
	v_pk_mul_f32 v[110:111], v[110:111], v[220:221]
	v_pk_mul_f32 v[112:113], v[112:113], v[222:223]
	v_pk_mul_f32 v[106:107], v[106:107], v[216:217]
	v_pk_mul_f32 v[108:109], v[108:109], v[218:219]
	v_pk_mul_f32 v[106:107], v[98:99], v[106:107]
	v_pk_mul_f32 v[100:101], v[100:101], v[108:109]
	v_pk_mul_f32 v[102:103], v[102:103], v[110:111]
	v_pk_mul_f32 v[104:105], v[104:105], v[112:113]
	v_cvt_pk_bf16_f32 v98, v102, v103
	v_cvt_pk_bf16_f32 v99, v104, v105
	v_cvt_pk_bf16_f32 v101, v100, v101
	v_cvt_pk_bf16_f32 v100, v106, v107
	ds_write_b128 v162, v[98:101]
	ds_read_b128 v[98:101], v163
	v_add_co_u32_e32 v102, vcc, s41, v114
	s_nop 1
	v_addc_co_u32_e32 v103, vcc, 0, v115, vcc
	s_waitcnt lgkmcnt(0)
; __device__ __forceinline__ unsigned cvt_pk_bf16(float lo, float hi) { unsigned r; asm volatile("v_cvt_pk_bf16_f32 %0, %1, %2" : "=v"(r) : "v"(lo), "v"(hi)); return r; }
; #define LAS __attribute__((address_space(3)))
; __device__ __forceinline__ float rstd_of(float ss) { return __builtin_amdgcn_rsqf(ss * (1.0f / DM) + EPS); }
; __device__ __forceinline__ float siluf_(float x) { return x * __builtin_amdgcn_rcpf(1.0f + __builtin_amdgcn_exp2f(-1.4426950408889634f * x)); }
;     __device__ __forceinline__ void operator()(const pg8::f32x4 (&acc)[2][2][4][2], const Unit& u, int wr, int wc, int fr, int fq) const {
;     ...
;             for (int m = 0; m < 4; ++m) { const int rg = ai * HALF + m * 16; const float rs = rstd_of(SS1[row0 + rg + fr]);
;                 const pg8::f32x4 g0 = acc[ai][0][m][0] * rs, g1 = acc[ai][0][m][1] * rs, u0 = acc[ai][1][m][0] * rs, u1 = acc[ai][1][m][1] * rs;
;                 u32x4 w; w.x = cvt_pk_bf16(siluf_(g0[0]) * u0[0], siluf_(g0[1]) * u0[1]); w.y = cvt_pk_bf16(siluf_(g0[2]) * u0[2], siluf_(g0[3]) * u0[3]);
;                 w.z = cvt_pk_bf16(siluf_(g1[0]) * u1[0], siluf_(g1[1]) * u1[1]); w.w = cvt_pk_bf16(siluf_(g1[2]) * u1[2], siluf_(g1[3]) * u1[3]);
;                 *(LAS u32x4*)epi_slot(W, fr, fq + 4 * (m & 1)) = w;
	global_store_dwordx4 v[102:103], v[98:101], off
	s_nop 1
	v_fmamk_f32 v98, v202, 0x3a800000, v159
	v_rsq_f32_e32 v98, v98
	s_nop 0
	v_pk_mul_f32 v[92:93], v[92:93], v[98:99] op_sel_hi:[1,0]
	v_pk_mul_f32 v[96:97], v[96:97], v[98:99] op_sel_hi:[1,0]
	v_pk_mul_f32 v[94:95], v[94:95], v[98:99] op_sel_hi:[1,0]
	v_pk_mul_f32 v[90:91], v[90:91], v[98:99] op_sel_hi:[1,0]
	v_pk_mul_f32 v[88:89], v[88:89], v[98:99] op_sel_hi:[1,0]
	v_pk_mul_f32 v[86:87], v[86:87], v[98:99] op_sel_hi:[1,0]
	v_pk_mul_f32 v[84:85], v[84:85], v[98:99] op_sel_hi:[1,0]
	v_pk_mul_f32 v[82:83], v[82:83], v[98:99] op_sel_hi:[1,0]
	v_pk_mul_f32 v[216:217], v[90:91], v[212:213] op_sel_hi:[1,0]
	v_pk_mul_f32 v[218:219], v[92:93], v[212:213] op_sel_hi:[1,0]
	v_pk_mul_f32 v[220:221], v[94:95], v[212:213] op_sel_hi:[1,0]
	v_pk_mul_f32 v[222:223], v[96:97], v[212:213] op_sel_hi:[1,0]
	v_exp_f32_e32 v219, v219
	v_exp_f32_e32 v220, v220
	v_exp_f32_e32 v221, v221
	v_exp_f32_e32 v222, v222
	v_exp_f32_e32 v223, v223
	v_exp_f32_e32 v216, v216
	v_exp_f32_e32 v217, v217
	v_exp_f32_e32 v218, v218
	v_pk_add_f32 v[220:221], v[220:221], v[214:215] op_sel_hi:[1,0]
	v_pk_add_f32 v[222:223], v[222:223], v[214:215] op_sel_hi:[1,0]
	v_pk_add_f32 v[216:217], v[216:217], v[214:215] op_sel_hi:[1,0]
	v_pk_add_f32 v[218:219], v[218:219], v[214:215] op_sel_hi:[1,0]
	v_rcp_f32_e32 v219, v219
	v_rcp_f32_e32 v220, v220
	v_rcp_f32_e32 v221, v221
	v_rcp_f32_e32 v222, v222
	v_rcp_f32_e32 v223, v223
	v_rcp_f32_e32 v216, v216
	v_rcp_f32_e32 v217, v217
	v_rcp_f32_e32 v218, v218
	v_pk_mul_f32 v[94:95], v[94:95], v[220:221]
	v_pk_mul_f32 v[96:97], v[96:97], v[222:223]
	v_pk_mul_f32 v[90:91], v[90:91], v[216:217]
	v_pk_mul_f32 v[92:93], v[92:93], v[218:219]
	v_pk_mul_f32 v[90:91], v[82:83], v[90:91]
	v_pk_mul_f32 v[84:85], v[84:85], v[92:93]
	v_pk_mul_f32 v[86:87], v[86:87], v[94:95]
	v_pk_mul_f32 v[88:89], v[88:89], v[96:97]
	v_cvt_pk_bf16_f32 v82, v86, v87
	v_cvt_pk_bf16_f32 v83, v88, v89
	v_cvt_pk_bf16_f32 v85, v84, v85
	v_cvt_pk_bf16_f32 v84, v90, v91
	ds_write_b128 v160, v[82:85]
	ds_read_b128 v[82:85], v161
	v_add_co_u32_e32 v86, vcc, s58, v114
	s_nop 1
	v_addc_co_u32_e32 v87, vcc, 0, v115, vcc
	s_waitcnt lgkmcnt(0)
	global_store_dwordx4 v[86:87], v[82:85], off
	s_nop 1
	v_fmamk_f32 v82, v203, 0x3a800000, v159
	v_rsq_f32_e32 v82, v82
	s_nop 0
	v_pk_mul_f32 v[76:77], v[76:77], v[82:83] op_sel_hi:[1,0]
	v_pk_mul_f32 v[80:81], v[80:81], v[82:83] op_sel_hi:[1,0]
	v_pk_mul_f32 v[78:79], v[78:79], v[82:83] op_sel_hi:[1,0]
	v_pk_mul_f32 v[74:75], v[74:75], v[82:83] op_sel_hi:[1,0]
	v_pk_mul_f32 v[72:73], v[72:73], v[82:83] op_sel_hi:[1,0]
	v_pk_mul_f32 v[70:71], v[70:71], v[82:83] op_sel_hi:[1,0]
	v_pk_mul_f32 v[68:69], v[68:69], v[82:83] op_sel_hi:[1,0]
	v_pk_mul_f32 v[66:67], v[66:67], v[82:83] op_sel_hi:[1,0]
	v_pk_mul_f32 v[216:217], v[74:75], v[212:213] op_sel_hi:[1,0]
	v_pk_mul_f32 v[218:219], v[76:77], v[212:213] op_sel_hi:[1,0]
	v_pk_mul_f32 v[220:221], v[78:79], v[212:213] op_sel_hi:[1,0]
	v_pk_mul_f32 v[222:223], v[80:81], v[212:213] op_sel_hi:[1,0]
	v_exp_f32_e32 v219, v219
	v_exp_f32_e32 v220, v220
	v_exp_f32_e32 v221, v221
	v_exp_f32_e32 v222, v222
	v_exp_f32_e32 v223, v223
	v_exp_f32_e32 v216, v216
	v_exp_f32_e32 v217, v217
	v_exp_f32_e32 v218, v218
	v_pk_add_f32 v[220:221], v[220:221], v[214:215] op_sel_hi:[1,0]
	v_pk_add_f32 v[222:223], v[222:223], v[214:215] op_sel_hi:[1,0]
	v_pk_add_f32 v[216:217], v[216:217], v[214:215] op_sel_hi:[1,0]
	v_pk_add_f32 v[218:219], v[218:219], v[214:215] op_sel_hi:[1,0]
	v_rcp_f32_e32 v219, v219
	v_rcp_f32_e32 v220, v220
	v_rcp_f32_e32 v221, v221
	v_rcp_f32_e32 v222, v222
	v_rcp_f32_e32 v223, v223
	v_rcp_f32_e32 v216, v216
	v_rcp_f32_e32 v217, v217
	v_rcp_f32_e32 v218, v218
	v_pk_mul_f32 v[78:79], v[78:79], v[220:221]
	v_pk_mul_f32 v[80:81], v[80:81], v[222:223]
	v_pk_mul_f32 v[74:75], v[74:75], v[216:217]
	v_pk_mul_f32 v[76:77], v[76:77], v[218:219]
	v_pk_mul_f32 v[74:75], v[66:67], v[74:75]
	v_pk_mul_f32 v[68:69], v[68:69], v[76:77]
	v_pk_mul_f32 v[70:71], v[70:71], v[78:79]
	v_pk_mul_f32 v[72:73], v[72:73], v[80:81]
	v_cvt_pk_bf16_f32 v66, v70, v71
	v_cvt_pk_bf16_f32 v67, v72, v73
	v_cvt_pk_bf16_f32 v69, v68, v69
	v_cvt_pk_bf16_f32 v68, v74, v75
	ds_write_b128 v162, v[66:69]
	ds_read_b128 v[66:69], v163
	v_add_co_u32_e32 v70, vcc, s59, v114
	s_nop 1
	v_addc_co_u32_e32 v71, vcc, 0, v115, vcc
	s_waitcnt lgkmcnt(0)
	global_store_dwordx4 v[70:71], v[66:69], off
	s_nop 1
	v_fmamk_f32 v66, v204, 0x3a800000, v159
	v_rsq_f32_e32 v66, v66
	s_nop 0
	v_pk_mul_f32 v[60:61], v[60:61], v[66:67] op_sel_hi:[1,0]
	v_pk_mul_f32 v[64:65], v[64:65], v[66:67] op_sel_hi:[1,0]
	v_pk_mul_f32 v[62:63], v[62:63], v[66:67] op_sel_hi:[1,0]
	v_pk_mul_f32 v[58:59], v[58:59], v[66:67] op_sel_hi:[1,0]
	v_pk_mul_f32 v[56:57], v[56:57], v[66:67] op_sel_hi:[1,0]
	v_pk_mul_f32 v[54:55], v[54:55], v[66:67] op_sel_hi:[1,0]
	v_pk_mul_f32 v[52:53], v[52:53], v[66:67] op_sel_hi:[1,0]
	v_pk_mul_f32 v[50:51], v[50:51], v[66:67] op_sel_hi:[1,0]
	v_pk_mul_f32 v[216:217], v[58:59], v[212:213] op_sel_hi:[1,0]
	v_pk_mul_f32 v[218:219], v[60:61], v[212:213] op_sel_hi:[1,0]
	v_pk_mul_f32 v[220:221], v[62:63], v[212:213] op_sel_hi:[1,0]
	v_pk_mul_f32 v[222:223], v[64:65], v[212:213] op_sel_hi:[1,0]
	v_exp_f32_e32 v219, v219
	v_exp_f32_e32 v220, v220
	v_exp_f32_e32 v221, v221
	v_exp_f32_e32 v222, v222
	v_exp_f32_e32 v223, v223
	v_exp_f32_e32 v216, v216
	v_exp_f32_e32 v217, v217
	v_exp_f32_e32 v218, v218
	v_pk_add_f32 v[220:221], v[220:221], v[214:215] op_sel_hi:[1,0]
	v_pk_add_f32 v[222:223], v[222:223], v[214:215] op_sel_hi:[1,0]
	v_pk_add_f32 v[216:217], v[216:217], v[214:215] op_sel_hi:[1,0]
	v_pk_add_f32 v[218:219], v[218:219], v[214:215] op_sel_hi:[1,0]
	v_rcp_f32_e32 v219, v219
	v_rcp_f32_e32 v220, v220
	v_rcp_f32_e32 v221, v221
	v_rcp_f32_e32 v222, v222
	v_rcp_f32_e32 v223, v223
	v_rcp_f32_e32 v216, v216
	v_rcp_f32_e32 v217, v217
	v_rcp_f32_e32 v218, v218
	v_pk_mul_f32 v[62:63], v[62:63], v[220:221]
	v_pk_mul_f32 v[64:65], v[64:65], v[222:223]
	v_pk_mul_f32 v[58:59], v[58:59], v[216:217]
	v_pk_mul_f32 v[60:61], v[60:61], v[218:219]
	v_pk_mul_f32 v[58:59], v[50:51], v[58:59]
	v_pk_mul_f32 v[52:53], v[52:53], v[60:61]
	v_pk_mul_f32 v[54:55], v[54:55], v[62:63]
	v_pk_mul_f32 v[56:57], v[56:57], v[64:65]
	v_cvt_pk_bf16_f32 v50, v54, v55
	v_cvt_pk_bf16_f32 v51, v56, v57
	v_cvt_pk_bf16_f32 v53, v52, v53
	v_cvt_pk_bf16_f32 v52, v58, v59
	ds_write_b128 v160, v[50:53]
	ds_read_b128 v[50:53], v161
	v_add_co_u32_e32 v54, vcc, s60, v114
	s_nop 1
	v_addc_co_u32_e32 v55, vcc, 0, v115, vcc
	s_waitcnt lgkmcnt(0)
; __device__ __forceinline__ unsigned cvt_pk_bf16(float lo, float hi) { unsigned r; asm volatile("v_cvt_pk_bf16_f32 %0, %1, %2" : "=v"(r) : "v"(lo), "v"(hi)); return r; }
; #define LAS __attribute__((address_space(3)))
; __device__ __forceinline__ float rstd_of(float ss) { return __builtin_amdgcn_rsqf(ss * (1.0f / DM) + EPS); }
; __device__ __forceinline__ float siluf_(float x) { return x * __builtin_amdgcn_rcpf(1.0f + __builtin_amdgcn_exp2f(-1.4426950408889634f * x)); }
;     __device__ __forceinline__ void operator()(const pg8::f32x4 (&acc)[2][2][4][2], const Unit& u, int wr, int wc, int fr, int fq) const {
;     ...
;             for (int m = 0; m < 4; ++m) { const int rg = ai * HALF + m * 16; const float rs = rstd_of(SS1[row0 + rg + fr]);
;                 const pg8::f32x4 g0 = acc[ai][0][m][0] * rs, g1 = acc[ai][0][m][1] * rs, u0 = acc[ai][1][m][0] * rs, u1 = acc[ai][1][m][1] * rs;
;                 u32x4 w; w.x = cvt_pk_bf16(siluf_(g0[0]) * u0[0], siluf_(g0[1]) * u0[1]); w.y = cvt_pk_bf16(siluf_(g0[2]) * u0[2], siluf_(g0[3]) * u0[3]);
;                 w.z = cvt_pk_bf16(siluf_(g1[0]) * u1[0], siluf_(g1[1]) * u1[1]); w.w = cvt_pk_bf16(siluf_(g1[2]) * u1[2], siluf_(g1[3]) * u1[3]);
;                 *(LAS u32x4*)epi_slot(W, fr, fq + 4 * (m & 1)) = w;
	global_store_dwordx4 v[54:55], v[50:53], off
	s_nop 1
	v_fmamk_f32 v50, v205, 0x3a800000, v159
	v_rsq_f32_e32 v50, v50
	s_nop 0
	v_pk_mul_f32 v[44:45], v[44:45], v[50:51] op_sel_hi:[1,0]
	v_pk_mul_f32 v[48:49], v[48:49], v[50:51] op_sel_hi:[1,0]
	v_pk_mul_f32 v[46:47], v[46:47], v[50:51] op_sel_hi:[1,0]
	v_pk_mul_f32 v[42:43], v[42:43], v[50:51] op_sel_hi:[1,0]
	v_pk_mul_f32 v[40:41], v[40:41], v[50:51] op_sel_hi:[1,0]
	v_pk_mul_f32 v[38:39], v[38:39], v[50:51] op_sel_hi:[1,0]
	v_pk_mul_f32 v[36:37], v[36:37], v[50:51] op_sel_hi:[1,0]
	v_pk_mul_f32 v[34:35], v[34:35], v[50:51] op_sel_hi:[1,0]
	v_pk_mul_f32 v[216:217], v[42:43], v[212:213] op_sel_hi:[1,0]
	v_pk_mul_f32 v[218:219], v[44:45], v[212:213] op_sel_hi:[1,0]
	v_pk_mul_f32 v[220:221], v[46:47], v[212:213] op_sel_hi:[1,0]
	v_pk_mul_f32 v[222:223], v[48:49], v[212:213] op_sel_hi:[1,0]
	v_exp_f32_e32 v219, v219
	v_exp_f32_e32 v220, v220
	v_exp_f32_e32 v221, v221
	v_exp_f32_e32 v222, v222
	v_exp_f32_e32 v223, v223
	v_exp_f32_e32 v216, v216
	v_exp_f32_e32 v217, v217
	v_exp_f32_e32 v218, v218
	v_pk_add_f32 v[220:221], v[220:221], v[214:215] op_sel_hi:[1,0]
	v_pk_add_f32 v[222:223], v[222:223], v[214:215] op_sel_hi:[1,0]
	v_pk_add_f32 v[216:217], v[216:217], v[214:215] op_sel_hi:[1,0]
	v_pk_add_f32 v[218:219], v[218:219], v[214:215] op_sel_hi:[1,0]
	v_rcp_f32_e32 v219, v219
	v_rcp_f32_e32 v220, v220
	v_rcp_f32_e32 v221, v221
	v_rcp_f32_e32 v222, v222
	v_rcp_f32_e32 v223, v223
	v_rcp_f32_e32 v216, v216
	v_rcp_f32_e32 v217, v217
	v_rcp_f32_e32 v218, v218
	v_pk_mul_f32 v[46:47], v[46:47], v[220:221]
	v_pk_mul_f32 v[48:49], v[48:49], v[222:223]
	v_pk_mul_f32 v[42:43], v[42:43], v[216:217]
	v_pk_mul_f32 v[44:45], v[44:45], v[218:219]
	v_pk_mul_f32 v[42:43], v[34:35], v[42:43]
	v_pk_mul_f32 v[36:37], v[36:37], v[44:45]
	v_pk_mul_f32 v[38:39], v[38:39], v[46:47]
	v_pk_mul_f32 v[40:41], v[40:41], v[48:49]
	v_cvt_pk_bf16_f32 v34, v38, v39
	v_cvt_pk_bf16_f32 v35, v40, v41
	v_cvt_pk_bf16_f32 v37, v36, v37
	v_cvt_pk_bf16_f32 v36, v42, v43
	ds_write_b128 v162, v[34:37]
	ds_read_b128 v[34:37], v163
	v_add_co_u32_e32 v38, vcc, s61, v114
	s_nop 1
	v_addc_co_u32_e32 v39, vcc, 0, v115, vcc
	s_waitcnt lgkmcnt(0)
	global_store_dwordx4 v[38:39], v[34:37], off
	s_nop 1
	v_fmamk_f32 v34, v206, 0x3a800000, v159
	v_rsq_f32_e32 v34, v34
	s_nop 0
	v_pk_mul_f32 v[28:29], v[28:29], v[34:35] op_sel_hi:[1,0]
	v_pk_mul_f32 v[32:33], v[32:33], v[34:35] op_sel_hi:[1,0]
	v_pk_mul_f32 v[30:31], v[30:31], v[34:35] op_sel_hi:[1,0]
	v_pk_mul_f32 v[26:27], v[26:27], v[34:35] op_sel_hi:[1,0]
	v_pk_mul_f32 v[24:25], v[24:25], v[34:35] op_sel_hi:[1,0]
	v_pk_mul_f32 v[22:23], v[22:23], v[34:35] op_sel_hi:[1,0]
	v_pk_mul_f32 v[20:21], v[20:21], v[34:35] op_sel_hi:[1,0]
	v_pk_mul_f32 v[18:19], v[18:19], v[34:35] op_sel_hi:[1,0]
	v_pk_mul_f32 v[216:217], v[26:27], v[212:213] op_sel_hi:[1,0]
	v_pk_mul_f32 v[218:219], v[28:29], v[212:213] op_sel_hi:[1,0]
	v_pk_mul_f32 v[220:221], v[30:31], v[212:213] op_sel_hi:[1,0]
	v_pk_mul_f32 v[222:223], v[32:33], v[212:213] op_sel_hi:[1,0]
	v_exp_f32_e32 v219, v219
	v_exp_f32_e32 v220, v220
	v_exp_f32_e32 v221, v221
	v_exp_f32_e32 v222, v222
	v_exp_f32_e32 v223, v223
	v_exp_f32_e32 v216, v216
	v_exp_f32_e32 v217, v217
	v_exp_f32_e32 v218, v218
	v_pk_add_f32 v[220:221], v[220:221], v[214:215] op_sel_hi:[1,0]
	v_pk_add_f32 v[222:223], v[222:223], v[214:215] op_sel_hi:[1,0]
	v_pk_add_f32 v[216:217], v[216:217], v[214:215] op_sel_hi:[1,0]
	v_pk_add_f32 v[218:219], v[218:219], v[214:215] op_sel_hi:[1,0]
	v_rcp_f32_e32 v219, v219
	v_rcp_f32_e32 v220, v220
	v_rcp_f32_e32 v221, v221
	v_rcp_f32_e32 v222, v222
	v_rcp_f32_e32 v223, v223
	v_rcp_f32_e32 v216, v216
	v_rcp_f32_e32 v217, v217
	v_rcp_f32_e32 v218, v218
	v_pk_mul_f32 v[30:31], v[30:31], v[220:221]
	v_pk_mul_f32 v[32:33], v[32:33], v[222:223]
	v_pk_mul_f32 v[26:27], v[26:27], v[216:217]
	v_pk_mul_f32 v[28:29], v[28:29], v[218:219]
	v_pk_mul_f32 v[26:27], v[18:19], v[26:27]
	v_pk_mul_f32 v[20:21], v[20:21], v[28:29]
	v_pk_mul_f32 v[22:23], v[22:23], v[30:31]
	v_pk_mul_f32 v[24:25], v[24:25], v[32:33]
	v_cvt_pk_bf16_f32 v18, v22, v23
	v_cvt_pk_bf16_f32 v19, v24, v25
	v_cvt_pk_bf16_f32 v21, v20, v21
	v_cvt_pk_bf16_f32 v20, v26, v27
	ds_write_b128 v160, v[18:21]
	ds_read_b128 v[18:21], v161
	v_add_co_u32_e32 v22, vcc, s62, v114
	s_nop 1
	v_addc_co_u32_e32 v23, vcc, 0, v115, vcc
	s_waitcnt lgkmcnt(0)
	global_store_dwordx4 v[22:23], v[18:21], off
	s_nop 1
	v_add_co_u32_e32 v20, vcc, 0xf2000, v114
	v_fmamk_f32 v18, v207, 0x3a800000, v159
	v_rsq_f32_e32 v18, v18
	s_nop 0
	v_pk_mul_f32 v[12:13], v[12:13], v[18:19] op_sel_hi:[1,0]
	v_pk_mul_f32 v[16:17], v[16:17], v[18:19] op_sel_hi:[1,0]
	v_pk_mul_f32 v[14:15], v[14:15], v[18:19] op_sel_hi:[1,0]
	v_pk_mul_f32 v[10:11], v[10:11], v[18:19] op_sel_hi:[1,0]
	v_pk_mul_f32 v[8:9], v[8:9], v[18:19] op_sel_hi:[1,0]
	v_pk_mul_f32 v[6:7], v[6:7], v[18:19] op_sel_hi:[1,0]
	v_pk_mul_f32 v[4:5], v[4:5], v[18:19] op_sel_hi:[1,0]
	v_pk_mul_f32 v[2:3], v[2:3], v[18:19] op_sel_hi:[1,0]
	v_pk_mul_f32 v[216:217], v[10:11], v[212:213] op_sel_hi:[1,0]
	v_pk_mul_f32 v[218:219], v[12:13], v[212:213] op_sel_hi:[1,0]
	v_pk_mul_f32 v[220:221], v[14:15], v[212:213] op_sel_hi:[1,0]
	v_pk_mul_f32 v[222:223], v[16:17], v[212:213] op_sel_hi:[1,0]
	v_exp_f32_e32 v219, v219
	v_exp_f32_e32 v220, v220
	v_exp_f32_e32 v221, v221
	v_exp_f32_e32 v222, v222
	v_exp_f32_e32 v223, v223
	v_exp_f32_e32 v216, v216
	v_exp_f32_e32 v217, v217
	v_exp_f32_e32 v218, v218
	v_pk_add_f32 v[220:221], v[220:221], v[214:215] op_sel_hi:[1,0]
	v_pk_add_f32 v[222:223], v[222:223], v[214:215] op_sel_hi:[1,0]
	v_pk_add_f32 v[216:217], v[216:217], v[214:215] op_sel_hi:[1,0]
	v_pk_add_f32 v[218:219], v[218:219], v[214:215] op_sel_hi:[1,0]
	v_rcp_f32_e32 v219, v219
	v_rcp_f32_e32 v220, v220
	v_rcp_f32_e32 v221, v221
	v_rcp_f32_e32 v222, v222
	v_rcp_f32_e32 v223, v223
	v_rcp_f32_e32 v216, v216
	v_rcp_f32_e32 v217, v217
	v_rcp_f32_e32 v218, v218
	v_pk_mul_f32 v[14:15], v[14:15], v[220:221]
	v_pk_mul_f32 v[16:17], v[16:17], v[222:223]
	v_pk_mul_f32 v[10:11], v[10:11], v[216:217]
	v_pk_mul_f32 v[12:13], v[12:13], v[218:219]
	v_pk_mul_f32 v[10:11], v[2:3], v[10:11]
	v_pk_mul_f32 v[4:5], v[4:5], v[12:13]
	v_pk_mul_f32 v[6:7], v[6:7], v[14:15]
	v_pk_mul_f32 v[8:9], v[8:9], v[16:17]
	v_cvt_pk_bf16_f32 v2, v6, v7
	v_cvt_pk_bf16_f32 v3, v8, v9
	v_cvt_pk_bf16_f32 v5, v4, v5
	v_cvt_pk_bf16_f32 v4, v10, v11
	ds_write_b128 v162, v[2:5]
	ds_read_b128 v[2:5], v163
	v_addc_co_u32_e32 v21, vcc, 0, v115, vcc
	s_andn2_b64 vcc, exec, s[0:1]
	s_mov_b64 s[0:1], -1
	s_waitcnt lgkmcnt(0)
	global_store_dwordx4 v[20:21], v[2:5], off
	s_cbranch_vccnz .LBB0_873
	s_andn2_b64 vcc, exec, s[12:13]
	s_cbranch_vccnz .LBB0_872
	s_barrier
	s_branch .LBB0_872
